# v81 with the barrier spin bound raised to 0x8000 polls (final candidate)
# speedup vs baseline: 1.0054x; 1.0041x over previous
.Lfb_poll_0:
	global_load_dword v5, v4, s[8:9] sc1
	s_waitcnt vmcnt(0)
	v_cmp_lt_u32_e32 vcc, v5, v0
	s_and_b64 vcc, exec, vcc
	s_cbranch_vccz .Lfb_done_0
	s_sleep 1
	s_add_i32 s13, s13, 1
	s_cmp_lt_u32 s13, 0x8000
	s_cbranch_scc1 .Lfb_poll_0
